# FFT stride-64 passes: the 16 LDS addresses of a radix-16 group use one base register plus immediate offsets (45 address instructions per iteration removed)
# baseline (speedup 1.0000x reference)
.LBB0_646:
	v_and_or_b32 v140, v111, s42, v0
	v_ashrrev_i32_e32 v114, 5, v140
	v_lshl_add_u32 v141, v140, 3, 0
	v_lshl_add_u32 v152, v114, 3, v141
	ds_read_b64 v[114:115], v152 offset:528
	ds_read_b64 v[116:117], v152 offset:1056
	ds_read_b64 v[118:119], v152 offset:1584
	ds_read_b64 v[120:121], v152 offset:2112
	ds_read_b64 v[122:123], v152 offset:2640
	ds_read_b64 v[124:125], v152 offset:3168
	ds_read_b64 v[126:127], v152 offset:3696
	ds_read_b64 v[128:129], v152 offset:4752
	ds_read_b64 v[130:131], v152 offset:5280
	ds_read_b64 v[132:133], v152 offset:5808
	ds_read_b64 v[134:135], v152 offset:6336
	ds_read_b64 v[136:137], v152 offset:6864
	ds_read_b64 v[138:139], v152 offset:7392
	ds_read_b64 v[140:141], v152 offset:7920
	ds_read_b64 v[142:143], v152 offset:4224
	ds_read_b64 v[144:145], v152
	v_add_u32_e32 v25, 0x200, v25
	v_cmp_lt_i32_e32 vcc, s35, v25
	v_add_u32_e32 v111, 0x2000, v111
	s_or_b64 s[10:11], vcc, s[10:11]
	s_waitcnt lgkmcnt(0)
	v_pk_add_f32 v[146:147], v[144:145], v[142:143] neg_lo:[0,1] neg_hi:[0,1]
	v_pk_add_f32 v[148:149], v[114:115], v[128:129] neg_lo:[0,1] neg_hi:[0,1]
	v_pk_add_f32 v[150:151], v[116:117], v[130:131] neg_lo:[0,1] neg_hi:[0,1]
	v_pk_add_f32 v[236:237], v[118:119], v[132:133] neg_lo:[0,1] neg_hi:[0,1]
	v_pk_add_f32 v[238:239], v[120:121], v[134:135] neg_lo:[0,1] neg_hi:[0,1]
	v_pk_add_f32 v[240:241], v[122:123], v[136:137] neg_lo:[0,1] neg_hi:[0,1]
	v_pk_add_f32 v[242:243], v[124:125], v[138:139] neg_lo:[0,1] neg_hi:[0,1]
	v_pk_add_f32 v[244:245], v[126:127], v[140:141] neg_lo:[0,1] neg_hi:[0,1]
	v_pk_mul_f32 v[246:247], v[20:21], v[146:147] op_sel:[0,1] op_sel_hi:[1,0]
	v_pk_add_f32 v[142:143], v[142:143], v[144:145]
	v_pk_mul_f32 v[144:145], v[40:41], v[148:149] op_sel:[0,1] op_sel_hi:[1,0]
	v_pk_fma_f32 v[146:147], v[2:3], v[146:147], v[246:247] neg_hi:[0,0,1]
	v_pk_mul_f32 v[246:247], v[44:45], v[150:151] op_sel:[0,1] op_sel_hi:[1,0]
	v_pk_add_f32 v[114:115], v[114:115], v[128:129]
	v_pk_mul_f32 v[128:129], v[48:49], v[236:237] op_sel:[0,1] op_sel_hi:[1,0]
	v_pk_fma_f32 v[144:145], v[38:39], v[148:149], v[144:145] neg_lo:[0,0,1]
	v_pk_mul_f32 v[148:149], v[52:53], v[238:239] op_sel:[0,1] op_sel_hi:[1,0]
	v_pk_add_f32 v[116:117], v[116:117], v[130:131]
	v_pk_mul_f32 v[130:131], v[22:23], v[240:241] op_sel:[0,1] op_sel_hi:[1,0]
	v_pk_fma_f32 v[150:151], v[42:43], v[150:151], v[246:247] neg_lo:[0,0,1]
	v_pk_mul_f32 v[246:247], v[34:35], v[242:243] op_sel:[0,1] op_sel_hi:[1,0]
	v_pk_add_f32 v[118:119], v[118:119], v[132:133]
	v_pk_mul_f32 v[132:133], v[58:59], v[244:245] op_sel:[0,1] op_sel_hi:[1,0]
	v_pk_fma_f32 v[128:129], v[32:33], v[236:237], v[128:129] neg_lo:[0,0,1]
	v_pk_add_f32 v[120:121], v[120:121], v[134:135]
	v_pk_fma_f32 v[134:135], v[50:51], v[238:239], v[148:149] neg_lo:[0,0,1]
	v_pk_add_f32 v[122:123], v[122:123], v[136:137]
	v_pk_fma_f32 v[136:137], v[46:47], v[240:241], v[130:131] neg_lo:[0,0,1]
	v_pk_add_f32 v[124:125], v[124:125], v[138:139]
	v_pk_fma_f32 v[138:139], v[36:37], v[242:243], v[246:247] neg_lo:[0,0,1]
	v_pk_add_f32 v[126:127], v[126:127], v[140:141]
	v_pk_fma_f32 v[140:141], v[30:31], v[244:245], v[132:133] neg_lo:[0,0,1]
	v_pk_add_f32 v[130:131], v[142:143], v[120:121] neg_lo:[0,1] neg_hi:[0,1]
	v_pk_add_f32 v[132:133], v[114:115], v[122:123] neg_lo:[0,1] neg_hi:[0,1]
	v_pk_add_f32 v[148:149], v[116:117], v[124:125] neg_lo:[0,1] neg_hi:[0,1]
	v_pk_add_f32 v[236:237], v[118:119], v[126:127] neg_lo:[0,1] neg_hi:[0,1]
	v_pk_add_f32 v[238:239], v[146:147], v[134:135] neg_lo:[0,1] neg_hi:[0,1]
	v_pk_add_f32 v[240:241], v[144:145], v[136:137] neg_lo:[0,1] neg_hi:[0,1]
	v_pk_add_f32 v[242:243], v[150:151], v[138:139] neg_lo:[0,1] neg_hi:[0,1]
	v_pk_add_f32 v[244:245], v[128:129], v[140:141] neg_lo:[0,1] neg_hi:[0,1]
	v_pk_mul_f32 v[246:247], v[56:57], v[130:131]
	v_pk_add_f32 v[120:121], v[120:121], v[142:143]
	v_pk_mul_f32 v[142:143], v[66:67], v[132:133]
	v_pk_fma_f32 v[130:131], v[54:55], v[130:131], v[246:247] op_sel:[0,0,1] op_sel_hi:[1,1,0] neg_hi:[0,0,1]
	v_pk_mul_f32 v[246:247], v[70:71], v[148:149]
	v_pk_add_f32 v[114:115], v[114:115], v[122:123]
	v_pk_mul_f32 v[122:123], v[60:61], v[236:237]
	v_pk_fma_f32 v[142:143], v[64:65], v[132:133], v[142:143] op_sel:[0,0,1] op_sel_hi:[1,1,0] neg_lo:[0,0,1]
	v_pk_mul_f32 v[132:133], v[56:57], v[238:239]
	v_pk_add_f32 v[116:117], v[116:117], v[124:125]
	v_pk_mul_f32 v[124:125], v[66:67], v[240:241]
	v_pk_fma_f32 v[148:149], v[68:69], v[148:149], v[246:247] op_sel:[0,0,1] op_sel_hi:[1,1,0] neg_lo:[0,0,1]
	v_pk_mul_f32 v[246:247], v[70:71], v[242:243]
	v_pk_add_f32 v[118:119], v[118:119], v[126:127]
	v_pk_mul_f32 v[126:127], v[60:61], v[244:245]
	v_pk_fma_f32 v[122:123], v[62:63], v[236:237], v[122:123] op_sel:[0,0,1] op_sel_hi:[1,1,0] neg_lo:[0,0,1]
	v_pk_add_f32 v[134:135], v[134:135], v[146:147]
	v_pk_fma_f32 v[132:133], v[54:55], v[238:239], v[132:133] op_sel:[0,0,1] op_sel_hi:[1,1,0] neg_hi:[0,0,1]
	v_pk_add_f32 v[136:137], v[144:145], v[136:137]
	v_pk_fma_f32 v[144:145], v[64:65], v[240:241], v[124:125] op_sel:[0,0,1] op_sel_hi:[1,1,0] neg_lo:[0,0,1]
	v_pk_add_f32 v[124:125], v[150:151], v[138:139]
	v_pk_fma_f32 v[138:139], v[68:69], v[242:243], v[246:247] op_sel:[0,0,1] op_sel_hi:[1,1,0] neg_lo:[0,0,1]
	v_pk_add_f32 v[128:129], v[128:129], v[140:141]
	v_pk_fma_f32 v[140:141], v[62:63], v[244:245], v[126:127] op_sel:[0,0,1] op_sel_hi:[1,1,0] neg_lo:[0,0,1]
	v_pk_add_f32 v[126:127], v[120:121], v[116:117] neg_lo:[0,1] neg_hi:[0,1]
	v_pk_add_f32 v[146:147], v[114:115], v[118:119] neg_lo:[0,1] neg_hi:[0,1]
	v_pk_add_f32 v[150:151], v[130:131], v[148:149] neg_lo:[0,1] neg_hi:[0,1]
	v_pk_add_f32 v[236:237], v[142:143], v[122:123] neg_lo:[0,1] neg_hi:[0,1]
	v_pk_add_f32 v[238:239], v[134:135], v[124:125] neg_lo:[0,1] neg_hi:[0,1]
	v_pk_add_f32 v[240:241], v[136:137], v[128:129] neg_lo:[0,1] neg_hi:[0,1]
	v_pk_add_f32 v[242:243], v[132:133], v[138:139] neg_lo:[0,1] neg_hi:[0,1]
	v_pk_add_f32 v[244:245], v[144:145], v[140:141] neg_lo:[0,1] neg_hi:[0,1]
	v_pk_mul_f32 v[246:247], v[74:75], v[126:127]
	v_pk_add_f32 v[116:117], v[116:117], v[120:121]
	v_pk_mul_f32 v[120:121], v[78:79], v[146:147]
	v_pk_fma_f32 v[126:127], v[72:73], v[126:127], v[246:247] op_sel:[0,0,1] op_sel_hi:[1,1,0] neg_hi:[0,0,1]
	v_pk_mul_f32 v[246:247], v[74:75], v[150:151]
	v_pk_add_f32 v[114:115], v[114:115], v[118:119]
	v_pk_mul_f32 v[118:119], v[78:79], v[236:237]
	v_pk_fma_f32 v[120:121], v[76:77], v[146:147], v[120:121] op_sel:[0,0,1] op_sel_hi:[1,1,0] neg_lo:[0,0,1]
	v_pk_mul_f32 v[146:147], v[74:75], v[238:239]
	v_pk_add_f32 v[130:131], v[148:149], v[130:131]
	v_pk_mul_f32 v[148:149], v[78:79], v[240:241]
	v_pk_fma_f32 v[150:151], v[72:73], v[150:151], v[246:247] op_sel:[0,0,1] op_sel_hi:[1,1,0] neg_hi:[0,0,1]
	v_pk_mul_f32 v[246:247], v[74:75], v[242:243]
	v_pk_add_f32 v[122:123], v[142:143], v[122:123]
	v_pk_mul_f32 v[142:143], v[78:79], v[244:245]
	v_pk_fma_f32 v[118:119], v[76:77], v[236:237], v[118:119] op_sel:[0,0,1] op_sel_hi:[1,1,0] neg_lo:[0,0,1]
	v_pk_add_f32 v[124:125], v[124:125], v[134:135]
	v_pk_fma_f32 v[134:135], v[72:73], v[238:239], v[146:147] op_sel:[0,0,1] op_sel_hi:[1,1,0] neg_hi:[0,0,1]
	v_pk_add_f32 v[128:129], v[136:137], v[128:129]
	v_pk_fma_f32 v[136:137], v[76:77], v[240:241], v[148:149] op_sel:[0,0,1] op_sel_hi:[1,1,0] neg_lo:[0,0,1]
	v_pk_add_f32 v[132:133], v[138:139], v[132:133]
	v_pk_fma_f32 v[148:149], v[72:73], v[242:243], v[246:247] op_sel:[0,0,1] op_sel_hi:[1,1,0] neg_hi:[0,0,1]
	v_pk_add_f32 v[138:139], v[144:145], v[140:141]
	v_pk_fma_f32 v[144:145], v[76:77], v[244:245], v[142:143] op_sel:[0,0,1] op_sel_hi:[1,1,0] neg_lo:[0,0,1]
	v_pk_add_f32 v[140:141], v[116:117], v[114:115] neg_lo:[0,1] neg_hi:[0,1]
	v_pk_add_f32 v[142:143], v[126:127], v[120:121] neg_lo:[0,1] neg_hi:[0,1]
	v_pk_add_f32 v[146:147], v[130:131], v[122:123] neg_lo:[0,1] neg_hi:[0,1]
	v_pk_add_f32 v[236:237], v[150:151], v[118:119] neg_lo:[0,1] neg_hi:[0,1]
	v_pk_add_f32 v[238:239], v[124:125], v[128:129] neg_lo:[0,1] neg_hi:[0,1]
	v_pk_add_f32 v[240:241], v[134:135], v[136:137] neg_lo:[0,1] neg_hi:[0,1]
	v_pk_add_f32 v[242:243], v[132:133], v[138:139] neg_lo:[0,1] neg_hi:[0,1]
	v_pk_add_f32 v[244:245], v[148:149], v[144:145] neg_lo:[0,1] neg_hi:[0,1]
	v_pk_mul_f32 v[246:247], v[82:83], v[140:141]
	v_pk_add_f32 v[114:115], v[114:115], v[116:117]
	v_pk_mul_f32 v[116:117], v[82:83], v[142:143]
	v_pk_fma_f32 v[140:141], v[80:81], v[140:141], v[246:247] op_sel:[0,0,1] op_sel_hi:[1,1,0] neg_hi:[0,0,1]
	v_pk_mul_f32 v[246:247], v[82:83], v[146:147]
	v_pk_add_f32 v[120:121], v[120:121], v[126:127]
	v_pk_mul_f32 v[126:127], v[82:83], v[236:237]
	v_pk_fma_f32 v[116:117], v[80:81], v[142:143], v[116:117] op_sel:[0,0,1] op_sel_hi:[1,1,0] neg_hi:[0,0,1]
	v_pk_mul_f32 v[142:143], v[82:83], v[238:239]
	v_pk_add_f32 v[122:123], v[122:123], v[130:131]
	v_pk_mul_f32 v[130:131], v[82:83], v[240:241]
	v_pk_fma_f32 v[146:147], v[80:81], v[146:147], v[246:247] op_sel:[0,0,1] op_sel_hi:[1,1,0] neg_hi:[0,0,1]
	v_pk_mul_f32 v[246:247], v[82:83], v[242:243]
	v_pk_add_f32 v[118:119], v[118:119], v[150:151]
	v_pk_mul_f32 v[150:151], v[82:83], v[244:245]
	v_pk_fma_f32 v[126:127], v[80:81], v[236:237], v[126:127] op_sel:[0,0,1] op_sel_hi:[1,1,0] neg_hi:[0,0,1]
	v_pk_add_f32 v[124:125], v[128:129], v[124:125]
	v_pk_fma_f32 v[142:143], v[80:81], v[238:239], v[142:143] op_sel:[0,0,1] op_sel_hi:[1,1,0] neg_hi:[0,0,1]
	v_pk_add_f32 v[128:129], v[136:137], v[134:135]
	v_pk_fma_f32 v[134:135], v[80:81], v[240:241], v[130:131] op_sel:[0,0,1] op_sel_hi:[1,1,0] neg_hi:[0,0,1]
	v_pk_add_f32 v[130:131], v[138:139], v[132:133]
	v_pk_fma_f32 v[132:133], v[80:81], v[242:243], v[246:247] op_sel:[0,0,1] op_sel_hi:[1,1,0] neg_hi:[0,0,1]
	v_pk_add_f32 v[136:137], v[144:145], v[148:149]
	v_pk_fma_f32 v[144:145], v[80:81], v[244:245], v[150:151] op_sel:[0,0,1] op_sel_hi:[1,1,0] neg_hi:[0,0,1]
	ds_write_b64 v152, v[114:115]
	ds_write_b64 v152, v[140:141] offset:528
	ds_write_b64 v152, v[120:121] offset:1056
	ds_write_b64 v152, v[116:117] offset:1584
	ds_write_b64 v152, v[122:123] offset:2112
	ds_write_b64 v152, v[146:147] offset:2640
	ds_write_b64 v152, v[118:119] offset:3168
	ds_write_b64 v152, v[126:127] offset:3696
	ds_write_b64 v152, v[124:125] offset:4224
	ds_write_b64 v152, v[142:143] offset:4752
	ds_write_b64 v152, v[128:129] offset:5280
	ds_write_b64 v152, v[134:135] offset:5808
	ds_write_b64 v152, v[130:131] offset:6336
	ds_write_b64 v152, v[132:133] offset:6864
	ds_write_b64 v152, v[136:137] offset:7392
	ds_write_b64 v152, v[144:145] offset:7920
	s_andn2_b64 exec, exec, s[10:11]
	s_cbranch_execnz .LBB0_646

.LBB0_666:
	v_and_or_b32 v140, v111, s42, v0
	v_ashrrev_i32_e32 v114, 5, v140
	v_lshl_add_u32 v141, v140, 3, 0
	v_lshl_add_u32 v152, v114, 3, v141
	ds_read_b64 v[114:115], v152 offset:528
	ds_read_b64 v[116:117], v152 offset:1056
	ds_read_b64 v[118:119], v152 offset:1584
	ds_read_b64 v[120:121], v152 offset:2112
	ds_read_b64 v[122:123], v152 offset:2640
	ds_read_b64 v[124:125], v152 offset:3168
	ds_read_b64 v[126:127], v152 offset:3696
	ds_read_b64 v[128:129], v152 offset:4752
	ds_read_b64 v[130:131], v152 offset:5280
	ds_read_b64 v[132:133], v152 offset:5808
	ds_read_b64 v[134:135], v152 offset:6336
	ds_read_b64 v[136:137], v152 offset:6864
	ds_read_b64 v[138:139], v152 offset:7392
	ds_read_b64 v[140:141], v152 offset:7920
	ds_read_b64 v[142:143], v152 offset:4224
	ds_read_b64 v[144:145], v152
	v_add_u32_e32 v25, 0x200, v25
	v_cmp_lt_i32_e32 vcc, s35, v25
	v_add_u32_e32 v111, 0x2000, v111
	s_or_b64 s[12:13], vcc, s[12:13]
	s_waitcnt lgkmcnt(0)
	v_pk_add_f32 v[146:147], v[144:145], v[142:143] neg_lo:[0,1] neg_hi:[0,1]
	v_pk_add_f32 v[148:149], v[114:115], v[128:129] neg_lo:[0,1] neg_hi:[0,1]
	v_pk_add_f32 v[150:151], v[116:117], v[130:131] neg_lo:[0,1] neg_hi:[0,1]
	v_pk_add_f32 v[236:237], v[118:119], v[132:133] neg_lo:[0,1] neg_hi:[0,1]
	v_pk_add_f32 v[238:239], v[120:121], v[134:135] neg_lo:[0,1] neg_hi:[0,1]
	v_pk_add_f32 v[240:241], v[122:123], v[136:137] neg_lo:[0,1] neg_hi:[0,1]
	v_pk_add_f32 v[242:243], v[124:125], v[138:139] neg_lo:[0,1] neg_hi:[0,1]
	v_pk_add_f32 v[244:245], v[126:127], v[140:141] neg_lo:[0,1] neg_hi:[0,1]
	v_pk_mul_f32 v[246:247], v[20:21], v[146:147] op_sel:[0,1] op_sel_hi:[1,0]
	v_pk_add_f32 v[142:143], v[142:143], v[144:145]
	v_pk_mul_f32 v[144:145], v[40:41], v[148:149] op_sel:[0,1] op_sel_hi:[1,0]
	v_pk_fma_f32 v[146:147], v[2:3], v[146:147], v[246:247] neg_hi:[0,0,1]
	v_pk_mul_f32 v[246:247], v[44:45], v[150:151] op_sel:[0,1] op_sel_hi:[1,0]
	v_pk_add_f32 v[114:115], v[114:115], v[128:129]
	v_pk_mul_f32 v[128:129], v[48:49], v[236:237] op_sel:[0,1] op_sel_hi:[1,0]
	v_pk_fma_f32 v[144:145], v[38:39], v[148:149], v[144:145] neg_lo:[0,0,1]
	v_pk_mul_f32 v[148:149], v[52:53], v[238:239] op_sel:[0,1] op_sel_hi:[1,0]
	v_pk_add_f32 v[116:117], v[116:117], v[130:131]
	v_pk_mul_f32 v[130:131], v[22:23], v[240:241] op_sel:[0,1] op_sel_hi:[1,0]
	v_pk_fma_f32 v[150:151], v[42:43], v[150:151], v[246:247] neg_lo:[0,0,1]
	v_pk_mul_f32 v[246:247], v[34:35], v[242:243] op_sel:[0,1] op_sel_hi:[1,0]
	v_pk_add_f32 v[118:119], v[118:119], v[132:133]
	v_pk_mul_f32 v[132:133], v[58:59], v[244:245] op_sel:[0,1] op_sel_hi:[1,0]
	v_pk_fma_f32 v[128:129], v[32:33], v[236:237], v[128:129] neg_lo:[0,0,1]
	v_pk_add_f32 v[120:121], v[120:121], v[134:135]
	v_pk_fma_f32 v[134:135], v[50:51], v[238:239], v[148:149] neg_lo:[0,0,1]
	v_pk_add_f32 v[122:123], v[122:123], v[136:137]
	v_pk_fma_f32 v[136:137], v[46:47], v[240:241], v[130:131] neg_lo:[0,0,1]
	v_pk_add_f32 v[124:125], v[124:125], v[138:139]
	v_pk_fma_f32 v[138:139], v[36:37], v[242:243], v[246:247] neg_lo:[0,0,1]
	v_pk_add_f32 v[126:127], v[126:127], v[140:141]
	v_pk_fma_f32 v[140:141], v[30:31], v[244:245], v[132:133] neg_lo:[0,0,1]
	v_pk_add_f32 v[130:131], v[142:143], v[120:121] neg_lo:[0,1] neg_hi:[0,1]
	v_pk_add_f32 v[132:133], v[114:115], v[122:123] neg_lo:[0,1] neg_hi:[0,1]
	v_pk_add_f32 v[148:149], v[116:117], v[124:125] neg_lo:[0,1] neg_hi:[0,1]
	v_pk_add_f32 v[236:237], v[118:119], v[126:127] neg_lo:[0,1] neg_hi:[0,1]
	v_pk_add_f32 v[238:239], v[146:147], v[134:135] neg_lo:[0,1] neg_hi:[0,1]
	v_pk_add_f32 v[240:241], v[144:145], v[136:137] neg_lo:[0,1] neg_hi:[0,1]
	v_pk_add_f32 v[242:243], v[150:151], v[138:139] neg_lo:[0,1] neg_hi:[0,1]
	v_pk_add_f32 v[244:245], v[128:129], v[140:141] neg_lo:[0,1] neg_hi:[0,1]
	v_pk_mul_f32 v[246:247], v[56:57], v[130:131]
	v_pk_add_f32 v[120:121], v[120:121], v[142:143]
	v_pk_mul_f32 v[142:143], v[66:67], v[132:133]
	v_pk_fma_f32 v[130:131], v[54:55], v[130:131], v[246:247] op_sel:[0,0,1] op_sel_hi:[1,1,0] neg_hi:[0,0,1]
	v_pk_mul_f32 v[246:247], v[70:71], v[148:149]
	v_pk_add_f32 v[114:115], v[114:115], v[122:123]
	v_pk_mul_f32 v[122:123], v[60:61], v[236:237]
	v_pk_fma_f32 v[142:143], v[64:65], v[132:133], v[142:143] op_sel:[0,0,1] op_sel_hi:[1,1,0] neg_lo:[0,0,1]
	v_pk_mul_f32 v[132:133], v[56:57], v[238:239]
	v_pk_add_f32 v[116:117], v[116:117], v[124:125]
	v_pk_mul_f32 v[124:125], v[66:67], v[240:241]
	v_pk_fma_f32 v[148:149], v[68:69], v[148:149], v[246:247] op_sel:[0,0,1] op_sel_hi:[1,1,0] neg_lo:[0,0,1]
	v_pk_mul_f32 v[246:247], v[70:71], v[242:243]
	v_pk_add_f32 v[118:119], v[118:119], v[126:127]
	v_pk_mul_f32 v[126:127], v[60:61], v[244:245]
	v_pk_fma_f32 v[122:123], v[62:63], v[236:237], v[122:123] op_sel:[0,0,1] op_sel_hi:[1,1,0] neg_lo:[0,0,1]
	v_pk_add_f32 v[134:135], v[134:135], v[146:147]
	v_pk_fma_f32 v[132:133], v[54:55], v[238:239], v[132:133] op_sel:[0,0,1] op_sel_hi:[1,1,0] neg_hi:[0,0,1]
	v_pk_add_f32 v[136:137], v[144:145], v[136:137]
	v_pk_fma_f32 v[144:145], v[64:65], v[240:241], v[124:125] op_sel:[0,0,1] op_sel_hi:[1,1,0] neg_lo:[0,0,1]
	v_pk_add_f32 v[124:125], v[150:151], v[138:139]
	v_pk_fma_f32 v[138:139], v[68:69], v[242:243], v[246:247] op_sel:[0,0,1] op_sel_hi:[1,1,0] neg_lo:[0,0,1]
	v_pk_add_f32 v[128:129], v[128:129], v[140:141]
	v_pk_fma_f32 v[140:141], v[62:63], v[244:245], v[126:127] op_sel:[0,0,1] op_sel_hi:[1,1,0] neg_lo:[0,0,1]
	v_pk_add_f32 v[126:127], v[120:121], v[116:117] neg_lo:[0,1] neg_hi:[0,1]
	v_pk_add_f32 v[146:147], v[114:115], v[118:119] neg_lo:[0,1] neg_hi:[0,1]
	v_pk_add_f32 v[150:151], v[130:131], v[148:149] neg_lo:[0,1] neg_hi:[0,1]
	v_pk_add_f32 v[236:237], v[142:143], v[122:123] neg_lo:[0,1] neg_hi:[0,1]
	v_pk_add_f32 v[238:239], v[134:135], v[124:125] neg_lo:[0,1] neg_hi:[0,1]
	v_pk_add_f32 v[240:241], v[136:137], v[128:129] neg_lo:[0,1] neg_hi:[0,1]
	v_pk_add_f32 v[242:243], v[132:133], v[138:139] neg_lo:[0,1] neg_hi:[0,1]
	v_pk_add_f32 v[244:245], v[144:145], v[140:141] neg_lo:[0,1] neg_hi:[0,1]
	v_pk_mul_f32 v[246:247], v[74:75], v[126:127]
	v_pk_add_f32 v[116:117], v[116:117], v[120:121]
	v_pk_mul_f32 v[120:121], v[78:79], v[146:147]
	v_pk_fma_f32 v[126:127], v[72:73], v[126:127], v[246:247] op_sel:[0,0,1] op_sel_hi:[1,1,0] neg_hi:[0,0,1]
	v_pk_mul_f32 v[246:247], v[74:75], v[150:151]
	v_pk_add_f32 v[114:115], v[114:115], v[118:119]
	v_pk_mul_f32 v[118:119], v[78:79], v[236:237]
	v_pk_fma_f32 v[120:121], v[76:77], v[146:147], v[120:121] op_sel:[0,0,1] op_sel_hi:[1,1,0] neg_lo:[0,0,1]
	v_pk_mul_f32 v[146:147], v[74:75], v[238:239]
	v_pk_add_f32 v[130:131], v[148:149], v[130:131]
	v_pk_mul_f32 v[148:149], v[78:79], v[240:241]
	v_pk_fma_f32 v[150:151], v[72:73], v[150:151], v[246:247] op_sel:[0,0,1] op_sel_hi:[1,1,0] neg_hi:[0,0,1]
	v_pk_mul_f32 v[246:247], v[74:75], v[242:243]
	v_pk_add_f32 v[122:123], v[142:143], v[122:123]
	v_pk_mul_f32 v[142:143], v[78:79], v[244:245]
	v_pk_fma_f32 v[118:119], v[76:77], v[236:237], v[118:119] op_sel:[0,0,1] op_sel_hi:[1,1,0] neg_lo:[0,0,1]
	v_pk_add_f32 v[124:125], v[124:125], v[134:135]
	v_pk_fma_f32 v[134:135], v[72:73], v[238:239], v[146:147] op_sel:[0,0,1] op_sel_hi:[1,1,0] neg_hi:[0,0,1]
	v_pk_add_f32 v[128:129], v[136:137], v[128:129]
	v_pk_fma_f32 v[136:137], v[76:77], v[240:241], v[148:149] op_sel:[0,0,1] op_sel_hi:[1,1,0] neg_lo:[0,0,1]
	v_pk_add_f32 v[132:133], v[138:139], v[132:133]
	v_pk_fma_f32 v[148:149], v[72:73], v[242:243], v[246:247] op_sel:[0,0,1] op_sel_hi:[1,1,0] neg_hi:[0,0,1]
	v_pk_add_f32 v[138:139], v[144:145], v[140:141]
	v_pk_fma_f32 v[144:145], v[76:77], v[244:245], v[142:143] op_sel:[0,0,1] op_sel_hi:[1,1,0] neg_lo:[0,0,1]
	v_pk_add_f32 v[140:141], v[116:117], v[114:115] neg_lo:[0,1] neg_hi:[0,1]
	v_pk_add_f32 v[142:143], v[126:127], v[120:121] neg_lo:[0,1] neg_hi:[0,1]
	v_pk_add_f32 v[146:147], v[130:131], v[122:123] neg_lo:[0,1] neg_hi:[0,1]
	v_pk_add_f32 v[236:237], v[150:151], v[118:119] neg_lo:[0,1] neg_hi:[0,1]
	v_pk_add_f32 v[238:239], v[124:125], v[128:129] neg_lo:[0,1] neg_hi:[0,1]
	v_pk_add_f32 v[240:241], v[134:135], v[136:137] neg_lo:[0,1] neg_hi:[0,1]
	v_pk_add_f32 v[242:243], v[132:133], v[138:139] neg_lo:[0,1] neg_hi:[0,1]
	v_pk_add_f32 v[244:245], v[148:149], v[144:145] neg_lo:[0,1] neg_hi:[0,1]
	v_pk_mul_f32 v[246:247], v[82:83], v[140:141]
	v_pk_add_f32 v[114:115], v[114:115], v[116:117]
	v_pk_mul_f32 v[116:117], v[82:83], v[142:143]
	v_pk_fma_f32 v[140:141], v[80:81], v[140:141], v[246:247] op_sel:[0,0,1] op_sel_hi:[1,1,0] neg_hi:[0,0,1]
	v_pk_mul_f32 v[246:247], v[82:83], v[146:147]
	v_pk_add_f32 v[120:121], v[120:121], v[126:127]
	v_pk_mul_f32 v[126:127], v[82:83], v[236:237]
	v_pk_fma_f32 v[116:117], v[80:81], v[142:143], v[116:117] op_sel:[0,0,1] op_sel_hi:[1,1,0] neg_hi:[0,0,1]
	v_pk_mul_f32 v[142:143], v[82:83], v[238:239]
	v_pk_add_f32 v[122:123], v[122:123], v[130:131]
	v_pk_mul_f32 v[130:131], v[82:83], v[240:241]
	v_pk_fma_f32 v[146:147], v[80:81], v[146:147], v[246:247] op_sel:[0,0,1] op_sel_hi:[1,1,0] neg_hi:[0,0,1]
	v_pk_mul_f32 v[246:247], v[82:83], v[242:243]
	v_pk_add_f32 v[118:119], v[118:119], v[150:151]
	v_pk_mul_f32 v[150:151], v[82:83], v[244:245]
	v_pk_fma_f32 v[126:127], v[80:81], v[236:237], v[126:127] op_sel:[0,0,1] op_sel_hi:[1,1,0] neg_hi:[0,0,1]
	v_pk_add_f32 v[124:125], v[128:129], v[124:125]
	v_pk_fma_f32 v[142:143], v[80:81], v[238:239], v[142:143] op_sel:[0,0,1] op_sel_hi:[1,1,0] neg_hi:[0,0,1]
	v_pk_add_f32 v[128:129], v[136:137], v[134:135]
	v_pk_fma_f32 v[134:135], v[80:81], v[240:241], v[130:131] op_sel:[0,0,1] op_sel_hi:[1,1,0] neg_hi:[0,0,1]
	v_pk_add_f32 v[130:131], v[138:139], v[132:133]
	v_pk_fma_f32 v[132:133], v[80:81], v[242:243], v[246:247] op_sel:[0,0,1] op_sel_hi:[1,1,0] neg_hi:[0,0,1]
	v_pk_add_f32 v[136:137], v[144:145], v[148:149]
	v_pk_fma_f32 v[144:145], v[80:81], v[244:245], v[150:151] op_sel:[0,0,1] op_sel_hi:[1,1,0] neg_hi:[0,0,1]
	ds_write_b64 v152, v[114:115]
	ds_write_b64 v152, v[140:141] offset:528
	ds_write_b64 v152, v[120:121] offset:1056
	ds_write_b64 v152, v[116:117] offset:1584
	ds_write_b64 v152, v[122:123] offset:2112
	ds_write_b64 v152, v[146:147] offset:2640
	ds_write_b64 v152, v[118:119] offset:3168
	ds_write_b64 v152, v[126:127] offset:3696
	ds_write_b64 v152, v[124:125] offset:4224
	ds_write_b64 v152, v[142:143] offset:4752
	ds_write_b64 v152, v[128:129] offset:5280
	ds_write_b64 v152, v[134:135] offset:5808
	ds_write_b64 v152, v[130:131] offset:6336
	ds_write_b64 v152, v[132:133] offset:6864
	ds_write_b64 v152, v[136:137] offset:7392
	ds_write_b64 v152, v[144:145] offset:7920
	s_andn2_b64 exec, exec, s[12:13]
	s_cbranch_execnz .LBB0_666

.LBB0_699:
	v_and_or_b32 v140, v111, s42, v0
	v_ashrrev_i32_e32 v114, 5, v140
	v_lshl_add_u32 v141, v140, 3, 0
	v_lshl_add_u32 v150, v114, 3, v141
	ds_read_b64 v[114:115], v150 offset:1056
	ds_read_b64 v[116:117], v150 offset:1584
	ds_read_b64 v[118:119], v150 offset:2112
	ds_read_b64 v[120:121], v150 offset:2640
	ds_read_b64 v[122:123], v150 offset:3168
	ds_read_b64 v[124:125], v150 offset:3696
	ds_read_b64 v[126:127], v150 offset:4224
	ds_read_b64 v[128:129], v150 offset:4752
	ds_read_b64 v[130:131], v150 offset:5280
	ds_read_b64 v[132:133], v150 offset:5808
	ds_read_b64 v[134:135], v150 offset:6336
	ds_read_b64 v[136:137], v150 offset:6864
	ds_read_b64 v[138:139], v150 offset:7392
	ds_read_b64 v[140:141], v150 offset:7920
	ds_read_b64 v[142:143], v150 offset:528
	ds_read_b64 v[144:145], v150
	v_add_u32_e32 v25, 0x200, v25
	v_cmp_lt_i32_e32 vcc, s35, v25
	v_add_u32_e32 v111, 0x2000, v111
	s_waitcnt lgkmcnt(1)
	v_pk_mul_f32 v[146:147], v[20:21], v[142:143]
	s_or_b64 s[12:13], vcc, s[12:13]
	v_pk_fma_f32 v[148:149], v[2:3], v[142:143], v[146:147] op_sel:[0,0,1] op_sel_hi:[1,1,0] neg_lo:[0,0,1]
	v_pk_mul_f32 v[146:147], v[20:21], v[116:117]
	s_waitcnt lgkmcnt(0)
	v_pk_add_f32 v[142:143], v[144:145], v[148:149]
	v_pk_add_f32 v[144:145], v[144:145], v[148:149] neg_lo:[0,1] neg_hi:[0,1]
	v_pk_fma_f32 v[148:149], v[2:3], v[116:117], v[146:147] op_sel:[0,0,1] op_sel_hi:[1,1,0] neg_lo:[0,0,1]
	v_pk_mul_f32 v[146:147], v[20:21], v[120:121]
	v_pk_add_f32 v[116:117], v[114:115], v[148:149]
	v_pk_add_f32 v[114:115], v[114:115], v[148:149] neg_lo:[0,1] neg_hi:[0,1]
	v_pk_fma_f32 v[148:149], v[2:3], v[120:121], v[146:147] op_sel:[0,0,1] op_sel_hi:[1,1,0] neg_lo:[0,0,1]
	v_pk_mul_f32 v[146:147], v[20:21], v[124:125]
	v_pk_add_f32 v[120:121], v[118:119], v[148:149]
	v_pk_add_f32 v[118:119], v[118:119], v[148:149] neg_lo:[0,1] neg_hi:[0,1]
	v_pk_fma_f32 v[148:149], v[2:3], v[124:125], v[146:147] op_sel:[0,0,1] op_sel_hi:[1,1,0] neg_lo:[0,0,1]
	v_pk_mul_f32 v[146:147], v[20:21], v[128:129]
	v_pk_add_f32 v[124:125], v[122:123], v[148:149]
	v_pk_add_f32 v[122:123], v[122:123], v[148:149] neg_lo:[0,1] neg_hi:[0,1]
	v_pk_fma_f32 v[148:149], v[2:3], v[128:129], v[146:147] op_sel:[0,0,1] op_sel_hi:[1,1,0] neg_lo:[0,0,1]
	v_pk_mul_f32 v[146:147], v[20:21], v[132:133]
	v_pk_add_f32 v[128:129], v[126:127], v[148:149]
	v_pk_add_f32 v[126:127], v[126:127], v[148:149] neg_lo:[0,1] neg_hi:[0,1]
	v_pk_fma_f32 v[148:149], v[2:3], v[132:133], v[146:147] op_sel:[0,0,1] op_sel_hi:[1,1,0] neg_lo:[0,0,1]
	v_pk_mul_f32 v[146:147], v[20:21], v[136:137]
	v_pk_add_f32 v[132:133], v[130:131], v[148:149]
	v_pk_add_f32 v[130:131], v[130:131], v[148:149] neg_lo:[0,1] neg_hi:[0,1]
	v_pk_fma_f32 v[148:149], v[2:3], v[136:137], v[146:147] op_sel:[0,0,1] op_sel_hi:[1,1,0] neg_lo:[0,0,1]
	v_pk_mul_f32 v[146:147], v[20:21], v[140:141]
	v_pk_add_f32 v[136:137], v[134:135], v[148:149]
	v_pk_add_f32 v[134:135], v[134:135], v[148:149] neg_lo:[0,1] neg_hi:[0,1]
	v_pk_fma_f32 v[148:149], v[2:3], v[140:141], v[146:147] op_sel:[0,0,1] op_sel_hi:[1,1,0] neg_lo:[0,0,1]
	v_pk_mul_f32 v[146:147], v[30:31], v[116:117]
	v_pk_add_f32 v[140:141], v[138:139], v[148:149]
	v_pk_add_f32 v[138:139], v[138:139], v[148:149] neg_lo:[0,1] neg_hi:[0,1]
	v_pk_fma_f32 v[148:149], v[22:23], v[116:117], v[146:147] op_sel:[0,0,1] op_sel_hi:[1,1,0] neg_lo:[0,0,1]
	v_pk_mul_f32 v[146:147], v[38:39], v[114:115]
	v_pk_add_f32 v[116:117], v[148:149], v[142:143]
	v_pk_add_f32 v[142:143], v[142:143], v[148:149] neg_lo:[0,1] neg_hi:[0,1]
	v_pk_fma_f32 v[148:149], v[36:37], v[114:115], v[146:147] op_sel:[0,0,1] op_sel_hi:[1,1,0] neg_hi:[0,0,1]
	v_pk_mul_f32 v[146:147], v[30:31], v[124:125]
	v_pk_add_f32 v[114:115], v[148:149], v[144:145]
	v_pk_add_f32 v[144:145], v[144:145], v[148:149] neg_lo:[0,1] neg_hi:[0,1]
	v_pk_fma_f32 v[148:149], v[22:23], v[124:125], v[146:147] op_sel:[0,0,1] op_sel_hi:[1,1,0] neg_lo:[0,0,1]
	v_pk_mul_f32 v[146:147], v[38:39], v[122:123]
	v_pk_add_f32 v[124:125], v[120:121], v[148:149]
	v_pk_add_f32 v[120:121], v[120:121], v[148:149] neg_lo:[0,1] neg_hi:[0,1]
	v_pk_fma_f32 v[148:149], v[36:37], v[122:123], v[146:147] op_sel:[0,0,1] op_sel_hi:[1,1,0] neg_hi:[0,0,1]
	v_pk_mul_f32 v[146:147], v[30:31], v[132:133]
	v_pk_add_f32 v[122:123], v[118:119], v[148:149]
	v_pk_add_f32 v[118:119], v[118:119], v[148:149] neg_lo:[0,1] neg_hi:[0,1]
	v_pk_fma_f32 v[148:149], v[22:23], v[132:133], v[146:147] op_sel:[0,0,1] op_sel_hi:[1,1,0] neg_lo:[0,0,1]
	v_pk_mul_f32 v[146:147], v[38:39], v[130:131]
	v_pk_add_f32 v[132:133], v[128:129], v[148:149]
	v_pk_add_f32 v[128:129], v[128:129], v[148:149] neg_lo:[0,1] neg_hi:[0,1]
	v_pk_fma_f32 v[148:149], v[36:37], v[130:131], v[146:147] op_sel:[0,0,1] op_sel_hi:[1,1,0] neg_hi:[0,0,1]
	v_pk_mul_f32 v[146:147], v[30:31], v[140:141]
	v_pk_add_f32 v[130:131], v[126:127], v[148:149]
	v_pk_add_f32 v[126:127], v[126:127], v[148:149] neg_lo:[0,1] neg_hi:[0,1]
	v_pk_fma_f32 v[148:149], v[22:23], v[140:141], v[146:147] op_sel:[0,0,1] op_sel_hi:[1,1,0] neg_lo:[0,0,1]
	v_pk_mul_f32 v[146:147], v[38:39], v[138:139]
	v_pk_add_f32 v[140:141], v[136:137], v[148:149]
	v_pk_add_f32 v[136:137], v[136:137], v[148:149] neg_lo:[0,1] neg_hi:[0,1]
	v_pk_fma_f32 v[148:149], v[36:37], v[138:139], v[146:147] op_sel:[0,0,1] op_sel_hi:[1,1,0] neg_hi:[0,0,1]
	v_pk_mul_f32 v[146:147], v[34:35], v[124:125]
	v_pk_add_f32 v[138:139], v[134:135], v[148:149]
	v_pk_add_f32 v[134:135], v[134:135], v[148:149] neg_lo:[0,1] neg_hi:[0,1]
	v_pk_fma_f32 v[148:149], v[32:33], v[124:125], v[146:147] op_sel:[0,0,1] op_sel_hi:[1,1,0] neg_lo:[0,0,1]
	v_pk_mul_f32 v[146:147], v[46:47], v[122:123]
	v_pk_add_f32 v[124:125], v[116:117], v[148:149]
	v_pk_add_f32 v[116:117], v[116:117], v[148:149] neg_lo:[0,1] neg_hi:[0,1]
	v_pk_fma_f32 v[148:149], v[44:45], v[122:123], v[146:147] op_sel:[0,0,1] op_sel_hi:[1,1,0] neg_hi:[0,0,1]
	v_pk_mul_f32 v[146:147], v[50:51], v[120:121]
	v_pk_add_f32 v[122:123], v[114:115], v[148:149]
	v_pk_add_f32 v[114:115], v[114:115], v[148:149] neg_lo:[0,1] neg_hi:[0,1]
	v_pk_fma_f32 v[148:149], v[48:49], v[120:121], v[146:147] op_sel:[0,0,1] op_sel_hi:[1,1,0] neg_hi:[0,0,1]
	v_pk_mul_f32 v[146:147], v[40:41], v[118:119]
	v_pk_add_f32 v[120:121], v[142:143], v[148:149]
	v_pk_add_f32 v[142:143], v[142:143], v[148:149] neg_lo:[0,1] neg_hi:[0,1]
	v_pk_fma_f32 v[148:149], v[42:43], v[118:119], v[146:147] op_sel:[0,0,1] op_sel_hi:[1,1,0] neg_hi:[0,0,1]
	v_pk_mul_f32 v[146:147], v[34:35], v[140:141]
	v_pk_add_f32 v[118:119], v[144:145], v[148:149]
	v_pk_add_f32 v[144:145], v[144:145], v[148:149] neg_lo:[0,1] neg_hi:[0,1]
	v_pk_fma_f32 v[148:149], v[32:33], v[140:141], v[146:147] op_sel:[0,0,1] op_sel_hi:[1,1,0] neg_lo:[0,0,1]
	v_pk_mul_f32 v[146:147], v[46:47], v[138:139]
	v_pk_add_f32 v[140:141], v[132:133], v[148:149]
	v_pk_add_f32 v[132:133], v[132:133], v[148:149] neg_lo:[0,1] neg_hi:[0,1]
	v_pk_fma_f32 v[148:149], v[44:45], v[138:139], v[146:147] op_sel:[0,0,1] op_sel_hi:[1,1,0] neg_hi:[0,0,1]
	v_pk_mul_f32 v[146:147], v[50:51], v[136:137]
	v_pk_add_f32 v[138:139], v[130:131], v[148:149]
	v_pk_add_f32 v[130:131], v[130:131], v[148:149] neg_lo:[0,1] neg_hi:[0,1]
	v_pk_fma_f32 v[148:149], v[48:49], v[136:137], v[146:147] op_sel:[0,0,1] op_sel_hi:[1,1,0] neg_hi:[0,0,1]
	v_pk_mul_f32 v[146:147], v[40:41], v[134:135]
	v_pk_add_f32 v[136:137], v[128:129], v[148:149]
	v_pk_add_f32 v[128:129], v[128:129], v[148:149] neg_lo:[0,1] neg_hi:[0,1]
	v_pk_fma_f32 v[148:149], v[42:43], v[134:135], v[146:147] op_sel:[0,0,1] op_sel_hi:[1,1,0] neg_hi:[0,0,1]
	v_pk_mul_f32 v[146:147], v[54:55], v[140:141] op_sel:[0,1] op_sel_hi:[1,0]
	v_pk_add_f32 v[134:135], v[126:127], v[148:149]
	v_pk_add_f32 v[126:127], v[126:127], v[148:149] neg_lo:[0,1] neg_hi:[0,1]
	v_pk_fma_f32 v[148:149], v[52:53], v[140:141], v[146:147] neg_lo:[0,0,1]
	v_pk_mul_f32 v[146:147], v[64:65], v[138:139] op_sel:[0,1] op_sel_hi:[1,0]
	v_pk_add_f32 v[140:141], v[124:125], v[148:149]
	v_pk_add_f32 v[124:125], v[124:125], v[148:149] neg_lo:[0,1] neg_hi:[0,1]
	v_pk_fma_f32 v[148:149], v[60:61], v[138:139], v[146:147] neg_hi:[0,0,1]
	v_pk_mul_f32 v[146:147], v[72:73], v[136:137] op_sel:[0,1] op_sel_hi:[1,0]
	v_pk_add_f32 v[138:139], v[122:123], v[148:149]
	v_pk_add_f32 v[122:123], v[122:123], v[148:149] neg_lo:[0,1] neg_hi:[0,1]
	v_pk_fma_f32 v[148:149], v[70:71], v[136:137], v[146:147] neg_hi:[0,0,1]
	v_pk_mul_f32 v[146:147], v[76:77], v[134:135] op_sel:[0,1] op_sel_hi:[1,0]
	v_pk_add_f32 v[136:137], v[120:121], v[148:149]
	v_pk_add_f32 v[120:121], v[120:121], v[148:149] neg_lo:[0,1] neg_hi:[0,1]
	v_pk_fma_f32 v[148:149], v[62:63], v[134:135], v[146:147] neg_hi:[0,0,1]
	v_pk_mul_f32 v[146:147], v[80:81], v[132:133] op_sel:[0,1] op_sel_hi:[1,0]
	v_pk_add_f32 v[134:135], v[118:119], v[148:149]
	v_pk_add_f32 v[118:119], v[118:119], v[148:149] neg_lo:[0,1] neg_hi:[0,1]
	v_pk_fma_f32 v[148:149], v[78:79], v[132:133], v[146:147] neg_hi:[0,0,1]
	v_pk_mul_f32 v[146:147], v[56:57], v[130:131] op_sel:[0,1] op_sel_hi:[1,0]
	v_pk_add_f32 v[132:133], v[116:117], v[148:149]
	v_pk_add_f32 v[116:117], v[116:117], v[148:149] neg_lo:[0,1] neg_hi:[0,1]
	v_pk_fma_f32 v[148:149], v[74:75], v[130:131], v[146:147] neg_hi:[0,0,1]
	v_pk_mul_f32 v[146:147], v[66:67], v[128:129] op_sel:[0,1] op_sel_hi:[1,0]
	v_pk_add_f32 v[130:131], v[114:115], v[148:149]
	v_pk_add_f32 v[114:115], v[114:115], v[148:149] neg_lo:[0,1] neg_hi:[0,1]
	v_pk_fma_f32 v[148:149], v[68:69], v[128:129], v[146:147] neg_hi:[0,0,1]
	v_pk_mul_f32 v[146:147], v[82:83], v[126:127] op_sel:[0,1] op_sel_hi:[1,0]
	v_pk_add_f32 v[128:129], v[142:143], v[148:149]
	v_pk_add_f32 v[142:143], v[142:143], v[148:149] neg_lo:[0,1] neg_hi:[0,1]
	v_pk_fma_f32 v[148:149], v[58:59], v[126:127], v[146:147] neg_hi:[0,0,1]
	s_nop 0
	v_pk_add_f32 v[126:127], v[144:145], v[148:149]
	v_pk_add_f32 v[144:145], v[144:145], v[148:149] neg_lo:[0,1] neg_hi:[0,1]
	ds_write_b64 v150, v[140:141]
	ds_write_b64 v150, v[138:139] offset:528
	ds_write_b64 v150, v[136:137] offset:1056
	ds_write_b64 v150, v[134:135] offset:1584
	ds_write_b64 v150, v[132:133] offset:2112
	ds_write_b64 v150, v[130:131] offset:2640
	ds_write_b64 v150, v[128:129] offset:3168
	ds_write_b64 v150, v[126:127] offset:3696
	ds_write_b64 v150, v[124:125] offset:4224
	ds_write_b64 v150, v[122:123] offset:4752
	ds_write_b64 v150, v[120:121] offset:5280
	ds_write_b64 v150, v[118:119] offset:5808
	ds_write_b64 v150, v[116:117] offset:6336
	ds_write_b64 v150, v[114:115] offset:6864
	ds_write_b64 v150, v[142:143] offset:7392
	ds_write_b64 v150, v[144:145] offset:7920
	s_andn2_b64 exec, exec, s[12:13]
	s_cbranch_execnz .LBB0_699
